# attn epilogue: attn_norm gains preloaded once per WG (7 serialized load+wait pairs removed); P0 xn loop: first-load wait moved below the 16 loads
# speedup vs baseline: 1.0081x; 1.0081x over previous
.LBB0_62:
	s_or_saveexec_b64 s[8:9], s[8:9]
	v_ashrrev_i32_e32 v89, 31, v88
	s_xor_b64 exec, exec, s[8:9]
	v_mov_b64_e32 v[18:19], v[88:89]
	s_or_b64 exec, exec, s[8:9]
	v_lshlrev_b64 v[18:19], 12, v[18:19]
	v_lshl_add_u64 v[18:19], v[20:21], 0, v[18:19]
	v_lshl_add_u64 v[18:19], v[18:19], 0, v[82:83]
	global_load_dwordx4 v[78:81], v[18:19], off
	global_load_dwordx4 v[74:77], v[18:19], off offset:1024
	global_load_dwordx4 v[66:69], v[18:19], off offset:3072
	global_load_dwordx4 v[70:73], v[18:19], off offset:2048
	v_add_co_u32_e32 v20, vcc, 0x1000, v18
	s_nop 1
	v_addc_co_u32_e32 v21, vcc, 0, v19, vcc
	v_add_co_u32_e32 v22, vcc, 0x2000, v18
	global_load_dwordx4 v[62:65], v[20:21], off
	global_load_dwordx4 v[58:61], v[20:21], off offset:1024
	global_load_dwordx4 v[54:57], v[20:21], off offset:2048
	global_load_dwordx4 v[50:53], v[20:21], off offset:3072
	v_addc_co_u32_e32 v23, vcc, 0, v19, vcc
	v_add_co_u32_e32 v18, vcc, 0x3000, v18
	global_load_dwordx4 v[46:49], v[22:23], off
	global_load_dwordx4 v[42:45], v[22:23], off offset:1024
	global_load_dwordx4 v[38:41], v[22:23], off offset:2048
	global_load_dwordx4 v[34:37], v[22:23], off offset:3072
	v_addc_co_u32_e32 v19, vcc, 0, v19, vcc
	global_load_dwordx4 v[30:33], v[18:19], off
	global_load_dwordx4 v[26:29], v[18:19], off offset:1024
	global_load_dwordx4 v[22:25], v[18:19], off offset:2048
	s_nop 0
	global_load_dwordx4 v[18:21], v[18:19], off offset:3072
	s_waitcnt vmcnt(15)
	v_pk_mul_f32 v[102:103], v[80:81], v[80:81]
	v_cmp_lt_i32_e32 vcc, v96, v95
	v_pk_mul_f32 v[104:105], v[78:79], v[78:79]
	s_waitcnt vmcnt(14)
	v_pk_mul_f32 v[106:107], v[76:77], v[76:77]
	v_pk_mul_f32 v[108:109], v[74:75], v[74:75]
	v_cndmask_b32_e32 v90, v94, v96, vcc
	v_pk_mov_b32 v[112:113], v[104:105], v[102:103] op_sel:[1,0]
	v_mov_b32_e32 v105, v103
	v_pk_mov_b32 v[102:103], v[108:109], v[106:107] op_sel:[1,0]
	v_mov_b32_e32 v109, v107
	v_lshlrev_b32_e32 v101, 2, v90
	s_waitcnt vmcnt(12)
	v_mul_f32_e32 v90, v71, v71
	v_mul_f32_e32 v110, v73, v73
	v_pk_add_f32 v[104:105], v[112:113], v[104:105]
	v_pk_add_f32 v[102:103], v[102:103], v[108:109]
	v_mul_f32_e32 v114, v66, v66
	v_mul_f32_e32 v115, v67, v67
	v_mul_f32_e32 v116, v68, v68
	v_mul_f32_e32 v117, v69, v69
	v_pk_fma_f32 v[106:107], v[70:71], v[70:71], v[90:91] op_sel_hi:[1,1,0]
	v_pk_fma_f32 v[110:111], v[72:73], v[72:73], v[110:111] op_sel_hi:[1,1,0]
	v_pk_add_f32 v[104:105], v[104:105], v[104:105] op_sel:[0,1] op_sel_hi:[1,0]
	v_pk_add_f32 v[102:103], v[102:103], v[102:103] op_sel:[0,1] op_sel_hi:[1,0]
	v_mov_b32_e32 v107, v116
	v_mov_b32_e32 v111, v117
	v_mov_b32_e32 v105, v114
	v_mov_b32_e32 v103, v115
	v_pk_add_f32 v[102:103], v[104:105], v[102:103]
	v_pk_add_f32 v[104:105], v[106:107], v[110:111]
	v_cmp_lt_i32_e32 vcc, v97, v95
	v_pk_add_f32 v[102:103], v[102:103], v[104:105]
	s_nop 0
	v_add_f32_e32 v102, v102, v103
	ds_bpermute_b32 v103, v101, v102
	v_cndmask_b32_e32 v90, v94, v97, vcc
	v_lshlrev_b32_e32 v90, 2, v90
	v_cmp_lt_i32_e32 vcc, v98, v95
	s_waitcnt lgkmcnt(0)
	v_add_f32_e32 v102, v102, v103
	ds_bpermute_b32 v104, v90, v102
	v_cndmask_b32_e32 v103, v94, v98, vcc
	v_lshlrev_b32_e32 v103, 2, v103
	v_cmp_lt_i32_e32 vcc, v99, v95
	s_waitcnt lgkmcnt(0)
	v_add_f32_e32 v102, v102, v104
	ds_bpermute_b32 v105, v103, v102
	v_cndmask_b32_e32 v104, v94, v99, vcc
	v_lshlrev_b32_e32 v104, 2, v104
	v_cmp_lt_i32_e32 vcc, v100, v95
	s_waitcnt lgkmcnt(0)
	v_add_f32_e32 v102, v102, v105
	ds_bpermute_b32 v106, v104, v102
	v_cndmask_b32_e32 v105, v94, v100, vcc
	v_lshlrev_b32_e32 v105, 2, v105
	s_waitcnt lgkmcnt(0)
	v_add_f32_e32 v102, v102, v106
	ds_bpermute_b32 v107, v105, v102
	v_xor_b32_e32 v106, 32, v94
	v_cmp_lt_i32_e32 vcc, v106, v95
	s_waitcnt lgkmcnt(0)
	v_add_f32_e32 v102, v102, v107
	v_cndmask_b32_e32 v106, v94, v106, vcc
	v_lshlrev_b32_e32 v106, 2, v106
	ds_bpermute_b32 v107, v106, v102
	s_waitcnt lgkmcnt(0)
	v_add_f32_e32 v102, v102, v107
	v_fmamk_f32 v102, v102, 0x3a800000, v92
	s_and_saveexec_b64 s[10:11], s[0:1]
	s_cbranch_execz .LBB0_66
	v_mul_f32_e32 v107, 0x4f800000, v102
	v_cmp_gt_f32_e32 vcc, s25, v102
	s_nop 1
	v_cndmask_b32_e32 v107, v102, v107, vcc
	v_sqrt_f32_e32 v108, v107
	s_nop 0
	v_add_u32_e32 v109, -1, v108
	v_fma_f32 v111, -v109, v108, v107
	v_add_u32_e32 v110, 1, v108
	v_cmp_ge_f32_e64 s[8:9], 0, v111
	s_nop 1
	v_cndmask_b32_e64 v109, v108, v109, s[8:9]
	v_fma_f32 v108, -v110, v108, v107
	v_cmp_lt_f32_e64 s[8:9], 0, v108
	s_nop 1
	v_cndmask_b32_e64 v108, v109, v110, s[8:9]
	v_mul_f32_e32 v109, 0x37800000, v108
	v_cndmask_b32_e32 v108, v108, v109, vcc
	v_cmp_class_f32_e32 vcc, v107, v93
	s_nop 1
	v_cndmask_b32_e32 v107, v108, v107, vcc
	v_lshl_add_u64 v[108:109], v[88:89], 2, s[16:17]
	global_store_dword v[108:109], v107, off

.LBB0_385:
	s_movk_i32 s0, 0x100
	v_cmp_gt_u32_e64 s[34:35], s0, v0
	s_movk_i32 s0, 0xff
	v_cmp_lt_u32_e64 s[72:73], s0, v0
	s_movk_i32 s0, 0x300
	v_lshrrev_b32_e32 v6, 2, v0
	v_cmp_gt_u32_e64 s[84:85], s0, v0
	s_movk_i32 s0, 0x2ff
	v_and_b32_e32 v165, 8, v6
	v_lshrrev_b32_e32 v173, 4, v170
	v_cmp_lt_u32_e64 s[88:89], s0, v0
	v_or_b32_e32 v6, 0xc00, v0
	s_movk_i32 s0, 0xd00
	v_lshlrev_b32_e32 v170, 4, v0
	v_bfe_u32 v3, v0, 4, 2
	v_lshrrev_b32_e32 v179, 4, v6
	v_cmp_gt_u32_e64 s[94:95], s0, v6
	v_and_b32_e32 v6, 0xf0, v170
	v_and_b32_e32 v9, 62, v163
	v_add_u32_e32 v163, 0, v6
	v_add_u32_e32 v187, 0, v2
	v_lshlrev_b32_e32 v6, 2, v3
	v_and_b32_e32 v2, 16, v0
	v_or_b32_e32 v8, 64, v160
	s_movk_i32 s55, 0x1d8
	v_readlane_b32 s16, v252, 1
	v_lshlrev_b32_e32 v5, 6, v185
	v_mov_b32_e32 v91, 0
	v_or_b32_e32 v180, 0xc0, v1
	s_movk_i32 s0, 0xd0
	v_mad_u32_u24 v191, v8, s55, 0
	v_add_u32_e32 v8, 12, v6
	v_cmp_eq_u32_e32 vcc, 0, v2
	v_lshlrev_b32_e32 v90, 5, v160
	v_readlane_b32 s24, v252, 9
	v_readlane_b32 s25, v252, 10
	v_lshrrev_b32_e32 v168, 4, v168
	v_lshrrev_b32_e32 v177, 4, v177
	v_cmp_gt_u32_e64 s[56:57], s0, v180
	s_movk_i32 s0, 0x110
	v_or_b32_e32 v11, v6, v5
	v_cndmask_b32_e32 v8, v8, v6, vcc
	v_add_u32_e32 v10, 44, v6
	v_or_b32_e32 v6, 32, v6
	v_lshl_add_u64 v[92:93], s[24:25], 0, v[90:91]
	v_lshlrev_b32_e32 v90, 4, v3
	v_lshlrev_b32_e32 v164, 3, v3
	v_mul_lo_u32 v182, v168, s0
	v_mul_lo_u32 v183, v173, s0
	v_mul_lo_u32 v184, v177, s0
	v_mad_u32_u24 v189, v160, s55, 0
	s_mov_b32 s0, 0xdd00
	v_cndmask_b32_e32 v10, v10, v6, vcc
	v_lshl_add_u64 v[12:13], s[80:81], 0, v[90:91]
	v_lshlrev_b32_e32 v90, 4, v160
	v_or_b32_e32 v7, 0x100, v5
	v_add3_u32 v190, v189, v164, s0
	v_or_b32_e32 v2, v8, v5
	v_or_b32_e32 v6, v10, v5
	v_or_b32_e32 v5, 0x800, v0
	s_movk_i32 s0, 0x8ff
	v_lshl_add_u64 v[94:95], s[48:49], 0, v[90:91]
	v_lshlrev_b32_e32 v90, 2, v185
	v_cmp_lt_u32_e64 s[42:43], s0, v5
	s_movk_i32 s0, 0xb00
	v_lshl_add_u64 v[96:97], s[64:65], 0, v[90:91]
	v_lshlrev_b32_e32 v90, 2, v11
	v_or_b32_e32 v178, 0xa0, v1
	v_cmp_gt_u32_e64 s[4:5], s0, v5
	s_movk_i32 s0, 0xb0
	v_lshl_add_u64 v[98:99], s[66:67], 0, v[90:91]
	v_lshlrev_b32_e32 v90, 7, v185
	v_cmp_gt_u32_e64 s[70:71], s0, v178
	v_readlane_b32 s20, v252, 5
	v_readlane_b32 s21, v252, 6
	v_lshl_add_u64 v[12:13], v[12:13], 0, v[90:91]
	s_mov_b64 s[0:1], 0x1dc88800
	v_lshlrev_b32_e32 v90, 1, v2
	v_lshl_add_u64 v[100:101], v[12:13], 0, s[0:1]
	v_lshl_add_u64 v[12:13], s[80:81], 0, v[90:91]
	s_mov_b64 s[20:21], 0x23d48c00
	v_lshl_add_u64 v[104:105], v[12:13], 0, s[20:21]
	v_lshlrev_b32_e32 v12, 1, v6
	v_mov_b32_e32 v13, v91
	v_lshl_add_u64 v[14:15], s[80:81], 0, v[12:13]
	v_or_b32_e32 v90, 0x200, v90
	v_lshrrev_b32_e32 v194, 4, v5
	v_lshl_add_u64 v[106:107], v[14:15], 0, s[20:21]
	v_lshl_add_u64 v[14:15], s[80:81], 0, v[90:91]
	v_or_b32_e32 v90, 0x200, v12
	v_lshrrev_b32_e32 v103, 4, v0
	v_lshrrev_b32_e32 v162, 2, v160
	v_lshlrev_b32_e32 v4, 3, v160
	v_or_b32_e32 v176, 0x80, v1
	v_or_b32_e32 v8, v8, v7
	v_or_b32_e32 v10, v10, v7
	s_movk_i32 s59, 0x8f
	v_mul_u32_u24_e32 v5, 0x110, v194
	v_readlane_b32 s22, v252, 7
	v_readlane_b32 s23, v252, 8
	v_lshl_add_u64 v[12:13], s[80:81], 0, v[90:91]
	v_or_b32_e32 v166, 0x10100, v1
	v_or_b32_e32 v167, 0x10100, v103
	v_cmp_gt_u32_e64 s[74:75], 16, v1
	v_or_b32_e32 v169, 32, v1
	v_or_b32_e32 v171, 64, v103
	v_or_b32_e32 v172, 64, v1
	v_or_b32_e32 v174, 0x60, v1
	v_or_b32_e32 v175, 0x80, v103
	v_mul_u32_u24_e32 v181, 0x110, v103
	v_mul_u32_u24_e32 v186, 0x110, v179
	v_mul_u32_u24_e32 v188, 0x110, v160
	v_lshlrev_b32_e32 v192, 7, v1
	v_lshlrev_b32_e32 v193, 7, v103
	v_cmp_lt_u32_e64 s[68:69], s59, v176
	v_or_b32_e32 v195, 0x10000, v162
	s_mov_b64 s[22:23], s[4:5]
	v_add_u32_e32 v102, 0, v9
	v_lshl_add_u64 v[108:109], v[14:15], 0, s[20:21]
	v_lshl_add_u64 v[110:111], v[12:13], 0, s[20:21]
	s_add_i32 s62, 0, 0x23fc0
	s_movk_i32 s63, 0x407
	s_movk_i32 s64, 0x1e00
	s_mov_b32 s58, 0xf149f2ca
	s_mov_b32 s65, 0x3fb8aa3b
	v_mov_b32_e32 v185, 0x358637bd
	s_mov_b32 s66, 0x800000
	v_lshlrev_b32_e32 v112, 2, v4
	v_add_u32_e32 v196, v163, v5
	v_lshlrev_b32_e32 v114, 1, v2
	v_lshlrev_b32_e32 v116, 1, v6
	v_lshlrev_b32_e32 v118, 1, v8
	v_lshlrev_b32_e32 v120, 1, v10
	s_waitcnt vmcnt(12)
	v_mbcnt_hi_u32_b32 v211, -1, v204
	v_mov_b32_e32 v197, 0xf149f2ca
	v_mov_b32_e32 v198, v91
	v_mov_b32_e32 v199, v91
	v_mov_b32_e32 v200, v91
	v_mov_b32_e32 v201, v91
	v_readlane_b32 s17, v252, 2
	v_readlane_b32 s18, v252, 3
	v_readlane_b32 s19, v252, 4
	v_readlane_b32 s26, v252, 11
	v_readlane_b32 s27, v252, 12
	v_readlane_b32 s28, v252, 13
	v_readlane_b32 s29, v252, 14
	v_readlane_b32 s30, v252, 15
	v_readlane_b32 s31, v252, 16
	global_load_dwordx4 v[224:227], v[98:99], off offset:64
	global_load_dwordx4 v[228:231], v[98:99], off offset:128
	global_load_dwordx4 v[232:235], v[98:99], off offset:192
	global_load_dwordx4 v[236:239], v[98:99], off offset:1024
	global_load_dwordx4 v[240:243], v[98:99], off offset:1088
	global_load_dwordx4 v[244:247], v[98:99], off offset:1152
	global_load_dwordx4 v[248:251], v[98:99], off offset:1216
	s_branch .LBB0_389

.LBB0_414:
	v_add_u32_e32 v90, v187, v188
	ds_read_b128 v[34:37], v90
	ds_read_b128 v[38:41], v90 offset:64
	s_cmp_eq_u32 s24, 0
	s_cselect_b64 s[0:1], -1, 0
	v_cndmask_b32_e64 v53, v21, v5, s[0:1]
	v_cndmask_b32_e64 v52, v20, v4, s[0:1]
	v_cndmask_b32_e64 v51, v19, v3, s[0:1]
	v_cndmask_b32_e64 v50, v18, v2, s[0:1]
	v_cndmask_b32_e64 v149, v25, v9, s[0:1]
	v_cndmask_b32_e64 v148, v24, v8, s[0:1]
	s_waitcnt lgkmcnt(1)
	v_mfma_f32_16x16x32_bf16 v[34:37], v[34:37], v[50:53], 0
	v_cndmask_b32_e64 v147, v23, v7, s[0:1]
	v_cndmask_b32_e64 v146, v22, v6, s[0:1]
	global_load_dword v121, v[96:97], off
	ds_read_b128 v[42:45], v90 offset:39232
	s_waitcnt lgkmcnt(1)
	v_mfma_f32_16x16x32_bf16 v[150:153], v[38:41], v[146:149], v[34:37]
	ds_read_b128 v[38:41], v90 offset:4416
	ds_read_b128 v[46:49], v90 offset:43584
	ds_read_b128 v[202:205], v90 offset:47936
	ds_read_b128 v[34:37], v90 offset:4352
	s_waitcnt lgkmcnt(0)
	v_mfma_f32_16x16x32_bf16 v[34:37], v[34:37], v[50:53], 0
	s_waitcnt vmcnt(0)
	v_mul_f32_e32 v75, 0x3fb8aa3b, v121
	v_mfma_f32_16x16x32_bf16 v[154:157], v[38:41], v[146:149], v[34:37]
	ds_read_b128 v[38:41], v90 offset:8768
	s_nop 3
	ds_read_b128 v[34:37], v90 offset:8704
	s_waitcnt lgkmcnt(0)
	v_mfma_f32_16x16x32_bf16 v[34:37], v[34:37], v[50:53], 0
	v_mfma_f32_16x16x32_bf16 v[158:161], v[38:41], v[146:149], v[34:37]
	ds_read_b128 v[38:41], v90 offset:13120
	s_nop 5
	ds_read_b128 v[34:37], v90 offset:13056
	s_waitcnt lgkmcnt(0)
	v_mfma_f32_16x16x32_bf16 v[34:37], v[34:37], v[50:53], 0
	v_mfma_f32_16x16x32_bf16 v[70:73], v[38:41], v[146:149], v[34:37]
	ds_read_b128 v[38:41], v90 offset:17472
	s_nop 5
	ds_read_b128 v[34:37], v90 offset:17408
	s_waitcnt lgkmcnt(0)
	v_mfma_f32_16x16x32_bf16 v[34:37], v[34:37], v[50:53], 0
	v_add_f32_e64 v70, v86, v70
	v_add_f32_e64 v71, v87, v71
	v_mfma_f32_16x16x32_bf16 v[66:69], v[38:41], v[146:149], v[34:37]
	ds_read_b128 v[38:41], v90 offset:21824
	s_nop 3
	ds_read_b128 v[34:37], v90 offset:21760
	s_waitcnt lgkmcnt(0)
	v_mfma_f32_16x16x32_bf16 v[34:37], v[34:37], v[50:53], 0
	v_add_f32_e64 v66, v88, v66
	v_add_f32_e64 v67, v89, v67
	v_mfma_f32_16x16x32_bf16 v[62:65], v[38:41], v[146:149], v[34:37]
	ds_read_b128 v[38:41], v90 offset:26176
	s_nop 3
	ds_read_b128 v[34:37], v90 offset:26112
	s_waitcnt lgkmcnt(0)
	v_mfma_f32_16x16x32_bf16 v[34:37], v[34:37], v[50:53], 0
	v_add_f32_e64 v62, v124, v62
	v_add_f32_e64 v63, v125, v63
	v_mfma_f32_16x16x32_bf16 v[58:61], v[38:41], v[146:149], v[34:37]
	ds_read_b128 v[38:41], v90 offset:30528
	s_nop 3
	ds_read_b128 v[34:37], v90 offset:30464
	s_waitcnt lgkmcnt(0)
	v_mfma_f32_16x16x32_bf16 v[34:37], v[34:37], v[50:53], 0
	v_add_f32_e64 v58, v128, v58
	v_add_f32_e64 v59, v129, v59
	v_mfma_f32_16x16x32_bf16 v[54:57], v[38:41], v[146:149], v[34:37]
	ds_read_b128 v[38:41], v90 offset:34880
	s_nop 3
	ds_read_b128 v[34:37], v90 offset:34816
	s_waitcnt lgkmcnt(0)
	v_mfma_f32_16x16x32_bf16 v[34:37], v[34:37], v[50:53], 0
	v_add_f32_e64 v54, v132, v54
	v_add_f32_e64 v55, v133, v55
	v_mfma_f32_16x16x32_bf16 v[34:37], v[38:41], v[146:149], v[34:37]
	ds_read_b128 v[38:41], v90 offset:39168
	s_waitcnt lgkmcnt(0)
	v_mfma_f32_16x16x32_bf16 v[38:41], v[38:41], v[50:53], 0
	s_nop 4
	v_add_f32_e64 v34, v136, v34
	v_add_f32_e64 v35, v137, v35
	v_mfma_f32_16x16x32_bf16 v[38:41], v[42:45], v[146:149], v[38:41]
	ds_read_b128 v[42:45], v90 offset:43520
	s_waitcnt lgkmcnt(0)
	v_mfma_f32_16x16x32_bf16 v[42:45], v[42:45], v[50:53], 0
	s_nop 4
	v_add_f32_e64 v40, v40, 0
	v_add_f32_e64 v41, v41, 0
	v_pk_add_f32 v[38:39], v[38:39], 0 op_sel_hi:[1,0]
	v_mfma_f32_16x16x32_bf16 v[42:45], v[46:49], v[146:149], v[42:45]
	ds_read_b128 v[46:49], v90 offset:47872
	s_waitcnt lgkmcnt(0)
	v_mfma_f32_16x16x32_bf16 v[46:49], v[46:49], v[50:53], 0
	s_nop 4
	v_add_f32_e64 v44, v44, 0
	v_add_f32_e64 v45, v45, 0
	v_pk_add_f32 v[42:43], v[42:43], 0 op_sel_hi:[1,0]
	v_mfma_f32_16x16x32_bf16 v[46:49], v[202:205], v[146:149], v[46:49]
	ds_read_b128 v[202:205], v90 offset:52224
	s_waitcnt lgkmcnt(0)
	v_mfma_f32_16x16x32_bf16 v[50:53], v[202:205], v[50:53], 0
	ds_read_b128 v[202:205], v90 offset:52288
	s_nop 3
	v_pk_add_f32 v[48:49], v[48:49], 0 op_sel_hi:[1,0]
	v_pk_add_f32 v[46:47], v[46:47], 0 op_sel_hi:[1,0]
	s_waitcnt lgkmcnt(0)
	v_mfma_f32_16x16x32_bf16 v[50:53], v[202:205], v[146:149], v[50:53]
	v_add_f32_e64 v146, v152, 0
	v_add_f32_e64 v147, v153, 0
	v_pk_add_f32 v[148:149], v[150:151], 0 op_sel_hi:[1,0]
	v_max_f32_e32 v81, v146, v147
	v_max_f32_e32 v77, v148, v149
	v_max3_f32 v75, v75, v77, v81
	v_mov_b32_e32 v77, v76
	v_pk_add_f32 v[150:151], v[76:77], v[156:157]
	v_pk_add_f32 v[152:153], v[78:79], v[154:155]
	v_max_f32_e32 v85, v150, v151
	v_max_f32_e32 v81, v152, v153
	v_max3_f32 v75, v75, v81, v85
	v_mov_b32_e32 v81, v80
	v_pk_add_f32 v[154:155], v[80:81], v[160:161]
	v_pk_add_f32 v[156:157], v[82:83], v[158:159]
	v_max_f32_e32 v123, v154, v155
	v_max_f32_e32 v85, v156, v157
	v_max3_f32 v75, v75, v85, v123
	v_mov_b32_e32 v85, v84
	v_pk_add_f32 v[72:73], v[84:85], v[72:73]
	v_max_f32_e32 v123, v70, v71
	v_max_f32_e32 v127, v72, v73
	v_max3_f32 v123, v75, v123, v127
	v_mov_b32_e32 v75, v74
	v_pk_add_f32 v[68:69], v[74:75], v[68:69]
	v_max_f32_e32 v127, v66, v67
	v_max_f32_e32 v131, v68, v69
	v_max3_f32 v127, v123, v127, v131
	v_mov_b32_e32 v123, v122
	v_pk_add_f32 v[64:65], v[122:123], v[64:65]
	v_max_f32_e32 v131, v62, v63
	v_max_f32_e32 v135, v64, v65
	v_max3_f32 v131, v127, v131, v135
	v_mov_b32_e32 v127, v126
	v_pk_add_f32 v[60:61], v[126:127], v[60:61]
	v_max_f32_e32 v135, v58, v59
	v_max_f32_e32 v158, v60, v61
	v_max3_f32 v135, v131, v135, v158
	v_mov_b32_e32 v131, v130
	v_pk_add_f32 v[56:57], v[130:131], v[56:57]
	v_max_f32_e32 v158, v54, v55
	v_max_f32_e32 v159, v56, v57
	v_max3_f32 v158, v135, v158, v159
	v_mov_b32_e32 v135, v134
	v_pk_add_f32 v[36:37], v[134:135], v[36:37]
	v_max_f32_e32 v159, v34, v35
	v_max_f32_e32 v160, v36, v37
	v_max3_f32 v158, v158, v159, v160
	v_max_f32_e32 v159, v38, v39
	v_max_f32_e32 v160, v40, v41
	v_max3_f32 v158, v158, v159, v160
	v_max_f32_e32 v159, v42, v43
	v_max_f32_e32 v160, v44, v45
	v_max3_f32 v158, v158, v159, v160
	v_max_f32_e32 v159, v46, v47
	v_max_f32_e32 v160, v48, v49
	v_pk_add_f32 v[52:53], v[52:53], 0 op_sel_hi:[1,0]
	v_pk_add_f32 v[50:51], v[50:51], 0 op_sel_hi:[1,0]
	v_max3_f32 v158, v158, v159, v160
	v_max_f32_e32 v159, v50, v51
	v_max_f32_e32 v160, v52, v53
	v_max3_f32 v158, v158, v159, v160
	ds_bpermute_b32 v159, v113, v158
	s_waitcnt lgkmcnt(0)
	v_max_f32_e32 v159, v159, v159
	v_max_f32_e32 v158, v158, v159
	ds_bpermute_b32 v159, v115, v158
	s_waitcnt lgkmcnt(0)
	v_max_f32_e32 v159, v159, v159
	v_max_f32_e32 v210, v158, v159
	v_sub_f32_e32 v149, v149, v210
	v_sub_f32_e32 v146, v146, v210
	v_sub_f32_e32 v148, v148, v210
	v_exp_f32_e32 v158, v149
	v_exp_f32_e32 v149, v146
	v_sub_f32_e32 v146, v147, v210
	v_exp_f32_e32 v148, v148
	v_exp_f32_e32 v159, v146
	v_sub_f32_e32 v70, v70, v210
	v_sub_f32_e32 v67, v67, v210
	v_sub_f32_e32 v66, v66, v210
	v_pk_add_f32 v[146:147], v[148:149], v[158:159]
	v_exp_f32_e32 v66, v66
	v_add_f32_e32 v146, v146, v147
	v_add_f32_e32 v147, 0, v146
	v_sub_f32_e32 v146, v152, v210
	v_exp_f32_e32 v152, v146
	v_sub_f32_e32 v146, v153, v210
	v_exp_f32_e32 v160, v146
	v_sub_f32_e32 v146, v150, v210
	v_exp_f32_e32 v153, v146
	v_sub_f32_e32 v146, v151, v210
	v_exp_f32_e32 v161, v146
	v_sub_f32_e32 v146, v156, v210
	v_exp_f32_e32 v220, v146
	v_sub_f32_e32 v146, v157, v210
	v_pk_add_f32 v[150:151], v[152:153], v[160:161]
	v_exp_f32_e32 v221, v146
	v_sub_f32_e32 v146, v154, v210
	v_exp_f32_e32 v154, v70
	v_sub_f32_e32 v70, v71, v210
	v_pk_add_f32 v[150:151], v[150:151], v[150:151] op_sel_hi:[0,1]
	v_exp_f32_e32 v222, v146
	v_sub_f32_e32 v146, v155, v210
	v_exp_f32_e32 v156, v70
	v_sub_f32_e32 v70, v72, v210
	v_exp_f32_e32 v223, v146
	v_exp_f32_e32 v150, v70
	v_sub_f32_e32 v70, v73, v210
	v_exp_f32_e32 v146, v70
	v_add_f32_e32 v155, v220, v221
	v_add_f32_e32 v157, v222, v223
	v_pk_add_f32 v[70:71], v[154:155], v[156:157]
	v_pk_add_f32 v[72:73], v[150:151], v[146:147]
	v_sub_f32_e32 v62, v62, v210
	v_pk_add_f32 v[70:71], v[70:71], v[72:73]
	v_exp_f32_e32 v72, v67
	v_sub_f32_e32 v67, v68, v210
	v_sub_f32_e32 v68, v69, v210
	v_exp_f32_e32 v67, v67
	v_exp_f32_e32 v73, v68
	v_exp_f32_e32 v147, v62
	v_sub_f32_e32 v62, v63, v210
	v_exp_f32_e32 v151, v62
	v_sub_f32_e32 v62, v64, v210
	v_exp_f32_e32 v155, v62
	v_sub_f32_e32 v62, v65, v210
	v_sub_f32_e32 v58, v58, v210
	v_pk_add_f32 v[68:69], v[66:67], v[72:73]
	v_exp_f32_e32 v157, v62
	v_exp_f32_e32 v62, v58
	v_sub_f32_e32 v58, v59, v210
	v_pk_add_f32 v[68:69], v[68:69], v[68:69] op_sel_hi:[0,1]
	v_exp_f32_e32 v64, v58
	v_sub_f32_e32 v58, v60, v210
	v_pk_add_f32 v[70:71], v[70:71], v[70:71] op_sel_hi:[0,1]
	v_exp_f32_e32 v68, v58
	v_sub_f32_e32 v58, v61, v210
	v_exp_f32_e32 v70, v58
	v_add_f32_e32 v63, v147, v151
	v_add_f32_e32 v65, v155, v157
	v_pk_add_f32 v[58:59], v[62:63], v[64:65]
	v_pk_add_f32 v[60:61], v[68:69], v[70:71]
	v_sub_f32_e32 v55, v55, v210
	v_pk_add_f32 v[58:59], v[58:59], v[60:61]
	v_sub_f32_e32 v54, v54, v210
	v_exp_f32_e32 v60, v55
	v_sub_f32_e32 v55, v56, v210
	v_sub_f32_e32 v56, v57, v210
	v_sub_f32_e32 v34, v34, v210
	v_exp_f32_e32 v54, v54
	v_exp_f32_e32 v55, v55
	v_exp_f32_e32 v61, v56
	v_exp_f32_e32 v63, v34
	v_sub_f32_e32 v34, v35, v210
	v_exp_f32_e32 v65, v34
	v_sub_f32_e32 v34, v36, v210
	v_exp_f32_e32 v69, v34
	v_sub_f32_e32 v34, v37, v210
	v_exp_f32_e32 v71, v34
	v_sub_f32_e32 v34, v38, v210
	v_pk_add_f32 v[56:57], v[54:55], v[60:61]
	v_exp_f32_e32 v202, v34
	v_sub_f32_e32 v34, v39, v210
	v_pk_add_f32 v[56:57], v[56:57], v[56:57] op_sel_hi:[0,1]
	v_exp_f32_e32 v204, v34
	v_sub_f32_e32 v34, v40, v210
	v_pk_add_f32 v[58:59], v[58:59], v[58:59] op_sel_hi:[0,1]
	v_exp_f32_e32 v56, v34
	v_sub_f32_e32 v34, v41, v210
	v_exp_f32_e32 v58, v34
	v_add_f32_e32 v203, v63, v65
	v_add_f32_e32 v205, v69, v71
	v_pk_add_f32 v[34:35], v[202:203], v[204:205]
	v_pk_add_f32 v[36:37], v[56:57], v[58:59]
	s_nop 0
	v_pk_add_f32 v[34:35], v[34:35], v[36:37]
	s_nop 0
	v_pk_add_f32 v[206:207], v[34:35], v[34:35] op_sel_hi:[0,1]
	v_sub_f32_e32 v34, v42, v210
	v_exp_f32_e32 v208, v34
	v_sub_f32_e32 v34, v43, v210
	v_exp_f32_e32 v212, v34
	v_sub_f32_e32 v34, v44, v210
	v_exp_f32_e32 v209, v34
	v_sub_f32_e32 v34, v45, v210
	v_exp_f32_e32 v213, v34
	s_nop 0
	v_pk_add_f32 v[34:35], v[208:209], v[212:213]
	s_nop 0
	v_pk_add_f32 v[214:215], v[34:35], v[34:35] op_sel_hi:[0,1]
	v_sub_f32_e32 v34, v46, v210
	v_exp_f32_e32 v57, v34
	v_sub_f32_e32 v34, v47, v210
	v_exp_f32_e32 v59, v34
	v_sub_f32_e32 v34, v48, v210
	v_exp_f32_e32 v203, v34
	v_sub_f32_e32 v34, v49, v210
	v_exp_f32_e32 v205, v34
	v_sub_f32_e32 v34, v50, v210
	v_exp_f32_e32 v216, v34
	v_sub_f32_e32 v34, v51, v210
	v_exp_f32_e32 v218, v34
	v_sub_f32_e32 v34, v52, v210
	v_exp_f32_e32 v214, v34
	v_sub_f32_e32 v34, v53, v210
	v_exp_f32_e32 v206, v34
	v_add_f32_e32 v217, v57, v59
	v_add_f32_e32 v219, v203, v205
	v_pk_add_f32 v[34:35], v[216:217], v[218:219]
	v_pk_add_f32 v[36:37], v[214:215], v[206:207]
	s_nop 0
	v_pk_add_f32 v[34:35], v[34:35], v[36:37]
	s_nop 0
	v_add_f32_e32 v34, v34, v35
	ds_bpermute_b32 v35, v113, v34
	s_waitcnt lgkmcnt(0)
	v_add_f32_e32 v34, v34, v35
	ds_bpermute_b32 v35, v115, v34
	s_waitcnt lgkmcnt(0)
	v_add_f32_e32 v34, v34, v35
	v_fma_f32 v35, v121, s65, -v210
	v_exp_f32_e32 v35, v35
	s_nop 0
	v_add_f32_e32 v121, v35, v34
	v_cvt_pk_bf16_f32 v34, v148, v158
	v_cvt_pk_bf16_f32 v35, v149, v159
	v_cvt_pk_bf16_f32 v36, v152, v160
	v_cvt_pk_bf16_f32 v37, v153, v161
	v_cvt_pk_bf16_f32 v38, v220, v221
	v_cvt_pk_bf16_f32 v39, v222, v223
	v_cvt_pk_bf16_f32 v40, v154, v156
	v_cvt_pk_bf16_f32 v41, v150, v146
	v_cvt_pk_bf16_f32 v42, v66, v72
	v_cvt_pk_bf16_f32 v43, v67, v73
	v_cvt_pk_bf16_f32 v44, v147, v151
	v_cvt_pk_bf16_f32 v45, v155, v157
	v_cvt_pk_bf16_f32 v46, v62, v64
	v_div_scale_f32 v62, s[26:27], v121, v121, 1.0
	v_cvt_pk_bf16_f32 v47, v68, v70
	v_cvt_pk_bf16_f32 v48, v54, v60
	v_cvt_pk_bf16_f32 v49, v55, v61
	v_cvt_pk_bf16_f32 v50, v63, v65
	v_rcp_f32_e32 v63, v62
	v_add_u32_e32 v70, v189, v164
	v_cvt_pk_bf16_f32 v51, v69, v71
	v_add_u32_e32 v71, 0xd800, v70
	v_fma_f32 v64, -v62, v63, 1.0
	v_fmac_f32_e32 v63, v64, v63
	v_div_scale_f32 v64, vcc, 1.0, v121, 1.0
	v_mul_f32_e32 v65, v64, v63
	v_fma_f32 v66, -v62, v65, v64
	v_fmac_f32_e32 v65, v66, v63
	v_fma_f32 v62, -v62, v65, v64
	v_div_fmas_f32 v62, v62, v63, v65
	v_cvt_pk_bf16_f32 v52, v202, v204
	v_cvt_pk_bf16_f32 v53, v56, v58
	v_cvt_pk_bf16_f32 v54, v208, v212
	v_cvt_pk_bf16_f32 v55, v209, v213
	v_cvt_pk_bf16_f32 v56, v57, v59
	v_cvt_pk_bf16_f32 v57, v203, v205
	v_cvt_pk_bf16_f32 v58, v216, v218
	v_cvt_pk_bf16_f32 v59, v214, v206
	v_cvt_pk_bf16_f32 v60, v91, v91
	v_cvt_pk_bf16_f32 v61, v91, v91
	v_div_fixup_f32 v72, v62, v121, 1.0
	ds_read2_b64 v[62:65], v71 offset0:160 offset1:164
	ds_read2_b64 v[66:69], v71 offset0:168 offset1:172
	s_waitcnt lgkmcnt(1)
	v_mfma_f32_16x16x32_bf16 v[62:65], v[62:65], v[34:37], 0
	v_add_u32_e32 v70, 0xf800, v70
	ds_read_b128 v[154:157], v90 offset:21952
	ds_read_b128 v[158:161], v90 offset:26304
	s_waitcnt lgkmcnt(2)
	v_mfma_f32_16x16x32_bf16 v[62:65], v[66:69], v[38:41], v[62:65]
	ds_read2_b64 v[66:69], v71 offset0:176 offset1:180
	ds_read_b128 v[202:205], v90 offset:30656
	ds_read_b128 v[206:209], v90 offset:35008
	s_waitcnt lgkmcnt(2)
	v_mfma_f32_16x16x32_bf16 v[62:65], v[66:69], v[42:45], v[62:65]
	ds_read2_b64 v[66:69], v71 offset0:184 offset1:188
	ds_read_b128 v[212:215], v90 offset:39360
	ds_read_b128 v[216:219], v90 offset:43712
	s_waitcnt lgkmcnt(2)
	v_mfma_f32_16x16x32_bf16 v[62:65], v[66:69], v[46:49], v[62:65]
	ds_read2_b64 v[66:69], v71 offset0:192 offset1:196
	ds_read_b128 v[220:223], v90 offset:48064
	s_waitcnt lgkmcnt(1)
	v_mfma_f32_16x16x32_bf16 v[62:65], v[66:69], v[50:53], v[62:65]
	ds_read2_b64 v[66:69], v71 offset0:200 offset1:204
	s_waitcnt lgkmcnt(0)
	v_mfma_f32_16x16x32_bf16 v[62:65], v[66:69], v[54:57], v[62:65]
	ds_read2_b64 v[66:69], v71 offset0:208 offset1:212
	s_waitcnt lgkmcnt(0)
	v_mfma_f32_16x16x32_bf16 v[62:65], v[66:69], v[58:61], v[62:65]
	ds_read2_b64 v[66:69], v70 offset0:88 offset1:92
	s_nop 6
	v_pk_mul_f32 v[146:147], v[72:73], v[64:65] op_sel_hi:[0,1]
	v_pk_mul_f32 v[148:149], v[72:73], v[62:63] op_sel_hi:[0,1]
	ds_read2_b64 v[62:65], v70 offset0:80 offset1:84
	s_waitcnt lgkmcnt(0)
	v_mfma_f32_16x16x32_bf16 v[62:65], v[62:65], v[34:37], 0
	v_mfma_f32_16x16x32_bf16 v[62:65], v[66:69], v[38:41], v[62:65]
	ds_read2_b64 v[66:69], v70 offset0:96 offset1:100
	s_waitcnt lgkmcnt(0)
	v_mfma_f32_16x16x32_bf16 v[62:65], v[66:69], v[42:45], v[62:65]
	ds_read2_b64 v[66:69], v70 offset0:104 offset1:108
	s_waitcnt lgkmcnt(0)
	v_mfma_f32_16x16x32_bf16 v[62:65], v[66:69], v[46:49], v[62:65]
	ds_read2_b64 v[66:69], v70 offset0:112 offset1:116
	s_waitcnt lgkmcnt(0)
	v_mfma_f32_16x16x32_bf16 v[62:65], v[66:69], v[50:53], v[62:65]
	ds_read2_b64 v[66:69], v70 offset0:120 offset1:124
	s_waitcnt lgkmcnt(0)
	v_mfma_f32_16x16x32_bf16 v[62:65], v[66:69], v[54:57], v[62:65]
	ds_read2_b64 v[66:69], v70 offset0:128 offset1:132
	v_add_u32_e32 v70, 0x3800, v190
	ds_read2_b64 v[150:153], v70 offset0:104 offset1:108
	s_waitcnt lgkmcnt(1)
	v_mfma_f32_16x16x32_bf16 v[64:67], v[66:69], v[58:61], v[62:65]
	s_nop 7
	v_pk_mul_f32 v[62:63], v[72:73], v[66:67] op_sel_hi:[0,1]
	ds_read2_b64 v[66:69], v70 offset0:96 offset1:100
	s_waitcnt lgkmcnt(0)
	v_mfma_f32_16x16x32_bf16 v[66:69], v[66:69], v[34:37], 0
	v_mul_f32_e64 v64, v72, v64
	v_mul_f32_e64 v65, v72, v65
	v_mfma_f32_16x16x32_bf16 v[66:69], v[150:153], v[38:41], v[66:69]
	ds_read2_b64 v[150:153], v70 offset0:112 offset1:116
	s_waitcnt lgkmcnt(0)
	v_mfma_f32_16x16x32_bf16 v[66:69], v[150:153], v[42:45], v[66:69]
	ds_read2_b64 v[150:153], v70 offset0:120 offset1:124
	s_waitcnt lgkmcnt(0)
	v_mfma_f32_16x16x32_bf16 v[66:69], v[150:153], v[46:49], v[66:69]
	ds_read2_b64 v[150:153], v70 offset0:128 offset1:132
	s_waitcnt lgkmcnt(0)
	v_mfma_f32_16x16x32_bf16 v[66:69], v[150:153], v[50:53], v[66:69]
	ds_read2_b64 v[150:153], v70 offset0:136 offset1:140
	s_waitcnt lgkmcnt(0)
	v_mfma_f32_16x16x32_bf16 v[66:69], v[150:153], v[54:57], v[66:69]
	ds_read2_b64 v[150:153], v70 offset0:144 offset1:148
	v_add_u32_e32 v70, 0x5800, v190
	s_waitcnt lgkmcnt(0)
	v_mfma_f32_16x16x32_bf16 v[66:69], v[150:153], v[58:61], v[66:69]
	ds_read2_b64 v[150:153], v70 offset0:16 offset1:20
	s_nop 6
	v_pk_mul_f32 v[66:67], v[72:73], v[66:67] op_sel_hi:[0,1]
	s_waitcnt lgkmcnt(0)
	v_mfma_f32_16x16x32_bf16 v[34:37], v[150:153], v[34:37], 0
	ds_read2_b64 v[150:153], v70 offset0:24 offset1:28
	v_pk_mul_f32 v[68:69], v[72:73], v[68:69] op_sel_hi:[0,1]
	s_waitcnt lgkmcnt(0)
	v_mfma_f32_16x16x32_bf16 v[34:37], v[150:153], v[38:41], v[34:37]
	ds_read2_b64 v[38:41], v70 offset0:32 offset1:36
	ds_read_b128 v[150:153], v90 offset:17600
	s_waitcnt lgkmcnt(1)
	v_mfma_f32_16x16x32_bf16 v[34:37], v[38:41], v[42:45], v[34:37]
	ds_read2_b64 v[38:41], v70 offset0:40 offset1:44
	ds_read_b128 v[42:45], v90 offset:128
	s_waitcnt lgkmcnt(1)
	v_mfma_f32_16x16x32_bf16 v[34:37], v[38:41], v[46:49], v[34:37]
	ds_read2_b64 v[38:41], v70 offset0:48 offset1:52
	ds_read_b128 v[46:49], v90 offset:192
	s_waitcnt lgkmcnt(1)
	v_mfma_f32_16x16x32_bf16 v[34:37], v[38:41], v[50:53], v[34:37]
	ds_read2_b64 v[38:41], v70 offset0:56 offset1:60
	ds_read_b128 v[50:53], v90 offset:4544
	s_waitcnt lgkmcnt(1)
	v_mfma_f32_16x16x32_bf16 v[34:37], v[38:41], v[54:57], v[34:37]
	ds_read2_b64 v[38:41], v70 offset0:64 offset1:68
	ds_read_b128 v[54:57], v90 offset:8896
	s_waitcnt lgkmcnt(1)
	v_mfma_f32_16x16x32_bf16 v[34:37], v[38:41], v[58:61], v[34:37]
	v_cndmask_b32_e64 v41, v33, v17, s[0:1]
	v_cndmask_b32_e64 v40, v32, v16, s[0:1]
	v_cndmask_b32_e64 v39, v31, v15, s[0:1]
	s_nop 4
	v_pk_mul_f32 v[70:71], v[72:73], v[36:37] op_sel_hi:[0,1]
	v_pk_mul_f32 v[72:73], v[72:73], v[34:35] op_sel_hi:[0,1]
	v_cndmask_b32_e64 v37, v29, v13, s[0:1]
	v_cndmask_b32_e64 v36, v28, v12, s[0:1]
	v_cndmask_b32_e64 v35, v27, v11, s[0:1]
	v_cndmask_b32_e64 v34, v26, v10, s[0:1]
	v_cndmask_b32_e64 v38, v30, v14, s[0:1]
	ds_read_b128 v[58:61], v90 offset:13248
	v_mfma_f32_16x16x32_bf16 v[42:45], v[42:45], v[34:37], 0
	v_mfma_f32_16x16x32_bf16 v[42:45], v[46:49], v[38:41], v[42:45]
	ds_read_b128 v[46:49], v90 offset:4480
	s_waitcnt lgkmcnt(0)
	v_mfma_f32_16x16x32_bf16 v[46:49], v[46:49], v[34:37], 0
	v_mfma_f32_16x16x32_bf16 v[46:49], v[50:53], v[38:41], v[46:49]
	ds_read_b128 v[50:53], v90 offset:8832
	s_waitcnt lgkmcnt(0)
	v_mfma_f32_16x16x32_bf16 v[50:53], v[50:53], v[34:37], 0
	v_mfma_f32_16x16x32_bf16 v[50:53], v[54:57], v[38:41], v[50:53]
	ds_read_b128 v[54:57], v90 offset:13184
	s_waitcnt lgkmcnt(0)
	v_mfma_f32_16x16x32_bf16 v[54:57], v[54:57], v[34:37], 0
	v_mfma_f32_16x16x32_bf16 v[54:57], v[58:61], v[38:41], v[54:57]
	ds_read_b128 v[58:61], v90 offset:17536
	s_waitcnt lgkmcnt(0)
	v_mfma_f32_16x16x32_bf16 v[58:61], v[58:61], v[34:37], 0
	v_mfma_f32_16x16x32_bf16 v[58:61], v[150:153], v[38:41], v[58:61]
	ds_read_b128 v[150:153], v90 offset:21888
	s_waitcnt lgkmcnt(0)
	v_mfma_f32_16x16x32_bf16 v[150:153], v[150:153], v[34:37], 0
	v_mfma_f32_16x16x32_bf16 v[150:153], v[154:157], v[38:41], v[150:153]
	ds_read_b128 v[154:157], v90 offset:26240
	s_waitcnt lgkmcnt(0)
	v_mfma_f32_16x16x32_bf16 v[154:157], v[154:157], v[34:37], 0
	v_mfma_f32_16x16x32_bf16 v[154:157], v[158:161], v[38:41], v[154:157]
	ds_read_b128 v[158:161], v90 offset:30592
	s_waitcnt lgkmcnt(0)
	v_mfma_f32_16x16x32_bf16 v[158:161], v[158:161], v[34:37], 0
	v_mfma_f32_16x16x32_bf16 v[158:161], v[202:205], v[38:41], v[158:161]
	ds_read_b128 v[202:205], v90 offset:34944
	s_waitcnt lgkmcnt(0)
	v_mfma_f32_16x16x32_bf16 v[202:205], v[202:205], v[34:37], 0
	v_mfma_f32_16x16x32_bf16 v[202:205], v[206:209], v[38:41], v[202:205]
	ds_read_b128 v[206:209], v90 offset:39296
	s_waitcnt lgkmcnt(0)
	v_mfma_f32_16x16x32_bf16 v[206:209], v[206:209], v[34:37], 0
	v_mfma_f32_16x16x32_bf16 v[206:209], v[212:215], v[38:41], v[206:209]
	ds_read_b128 v[212:215], v90 offset:43648
	s_waitcnt lgkmcnt(0)
	v_mfma_f32_16x16x32_bf16 v[212:215], v[212:215], v[34:37], 0
	v_mfma_f32_16x16x32_bf16 v[212:215], v[216:219], v[38:41], v[212:215]
	ds_read_b128 v[216:219], v90 offset:48000
	s_waitcnt lgkmcnt(0)
	v_mfma_f32_16x16x32_bf16 v[216:219], v[216:219], v[34:37], 0
	v_mfma_f32_16x16x32_bf16 v[216:219], v[220:223], v[38:41], v[216:219]
	ds_read_b128 v[220:223], v90 offset:52352
	s_waitcnt lgkmcnt(0)
	v_mfma_f32_16x16x32_bf16 v[34:37], v[220:223], v[34:37], 0
	ds_read_b128 v[220:223], v90 offset:52416
	global_load_dword v90, v[96:97], off offset:16
	s_waitcnt vmcnt(0)
	v_mul_f32_e32 v121, 0x3fb8aa3b, v90
	s_waitcnt lgkmcnt(0)
	v_mfma_f32_16x16x32_bf16 v[34:37], v[220:223], v[38:41], v[34:37]
	v_add_f32_e64 v38, v44, 0
	v_add_f32_e64 v39, v45, 0
	v_pk_add_f32 v[40:41], v[42:43], 0 op_sel_hi:[1,0]
	v_max_f32_e32 v43, v38, v39
	v_max_f32_e32 v42, v40, v41
	v_max3_f32 v121, v121, v42, v43
	v_pk_add_f32 v[42:43], v[76:77], v[48:49]
	v_pk_add_f32 v[44:45], v[78:79], v[46:47]
	v_max_f32_e32 v47, v42, v43
	v_max_f32_e32 v46, v44, v45
	v_max3_f32 v77, v121, v46, v47
	v_pk_add_f32 v[46:47], v[80:81], v[52:53]
	v_pk_add_f32 v[48:49], v[82:83], v[50:51]
	v_max_f32_e32 v51, v46, v47
	v_max_f32_e32 v50, v48, v49
	v_max3_f32 v77, v77, v50, v51
	v_pk_add_f32 v[50:51], v[84:85], v[56:57]
	v_pk_add_f32 v[52:53], v[86:87], v[54:55]
	v_max_f32_e32 v55, v50, v51
	v_max_f32_e32 v54, v52, v53
	v_max3_f32 v77, v77, v54, v55
	v_pk_add_f32 v[54:55], v[74:75], v[60:61]
	v_pk_add_f32 v[56:57], v[88:89], v[58:59]
	v_max_f32_e32 v59, v54, v55
	v_max_f32_e32 v58, v56, v57
	v_max3_f32 v75, v77, v58, v59
	v_pk_add_f32 v[58:59], v[122:123], v[152:153]
	v_pk_add_f32 v[60:61], v[124:125], v[150:151]
	v_max_f32_e32 v81, v58, v59
	v_max_f32_e32 v77, v60, v61
	v_pk_add_f32 v[150:151], v[126:127], v[156:157]
	v_pk_add_f32 v[152:153], v[128:129], v[154:155]
	v_max3_f32 v75, v75, v77, v81
	v_max_f32_e32 v77, v152, v153
	v_max_f32_e32 v81, v150, v151
	v_pk_add_f32 v[154:155], v[130:131], v[160:161]
	v_pk_add_f32 v[156:157], v[132:133], v[158:159]
	v_max3_f32 v75, v75, v77, v81
	v_max_f32_e32 v77, v156, v157
	v_max_f32_e32 v81, v154, v155
	v_pk_add_f32 v[158:159], v[134:135], v[204:205]
	v_pk_add_f32 v[160:161], v[136:137], v[202:203]
	v_max3_f32 v75, v75, v77, v81
	v_max_f32_e32 v77, v160, v161
	v_max_f32_e32 v81, v158, v159
	v_pk_add_f32 v[202:203], v[208:209], 0 op_sel_hi:[1,0]
	v_pk_add_f32 v[204:205], v[206:207], 0 op_sel_hi:[1,0]
	v_max3_f32 v75, v75, v77, v81
	v_max_f32_e32 v77, v204, v205
	v_max_f32_e32 v81, v202, v203
	v_pk_add_f32 v[206:207], v[214:215], 0 op_sel_hi:[1,0]
	v_pk_add_f32 v[208:209], v[212:213], 0 op_sel_hi:[1,0]
	v_max3_f32 v75, v75, v77, v81
	v_max_f32_e32 v77, v208, v209
	v_max_f32_e32 v81, v206, v207
	v_pk_add_f32 v[212:213], v[218:219], 0 op_sel_hi:[1,0]
	v_pk_add_f32 v[214:215], v[216:217], 0 op_sel_hi:[1,0]
	v_max3_f32 v75, v75, v77, v81
	v_max_f32_e32 v77, v214, v215
	v_max_f32_e32 v81, v212, v213
	v_pk_add_f32 v[36:37], v[36:37], 0 op_sel_hi:[1,0]
	v_pk_add_f32 v[34:35], v[34:35], 0 op_sel_hi:[1,0]
	v_max3_f32 v75, v75, v77, v81
	v_max_f32_e32 v77, v34, v35
	v_max_f32_e32 v81, v36, v37
	v_max3_f32 v75, v75, v77, v81
	ds_bpermute_b32 v77, v113, v75
	s_waitcnt lgkmcnt(0)
	v_max_f32_e32 v77, v77, v77
	v_max_f32_e32 v75, v75, v77
	ds_bpermute_b32 v77, v115, v75
	s_waitcnt lgkmcnt(0)
	v_max_f32_e32 v77, v77, v77
	v_max_f32_e32 v75, v75, v77
	v_sub_f32_e32 v41, v41, v75
	v_sub_f32_e32 v38, v38, v75
	v_sub_f32_e32 v40, v40, v75
	v_exp_f32_e32 v216, v41
	v_exp_f32_e32 v41, v38
	v_sub_f32_e32 v38, v39, v75
	v_exp_f32_e32 v40, v40
	v_exp_f32_e32 v217, v38
	v_sub_f32_e32 v34, v34, v75
	v_pk_add_f32 v[38:39], v[40:41], v[216:217]
	s_nop 0
	v_add_f32_e32 v38, v38, v39
	v_add_f32_e32 v219, 0, v38
	v_sub_f32_e32 v38, v44, v75
	v_exp_f32_e32 v44, v38
	v_sub_f32_e32 v38, v45, v75
	v_exp_f32_e32 v220, v38
	v_sub_f32_e32 v38, v42, v75
	v_exp_f32_e32 v45, v38
	v_sub_f32_e32 v38, v43, v75
	v_exp_f32_e32 v221, v38
	s_nop 0
	v_pk_add_f32 v[38:39], v[44:45], v[220:221]
	s_nop 0
	v_pk_add_f32 v[222:223], v[38:39], v[38:39] op_sel_hi:[0,1]
	v_sub_f32_e32 v38, v48, v75
	v_exp_f32_e32 v77, v38
	v_sub_f32_e32 v38, v49, v75
	v_exp_f32_e32 v81, v38
	v_sub_f32_e32 v38, v46, v75
	v_exp_f32_e32 v85, v38
	v_sub_f32_e32 v38, v47, v75
	v_exp_f32_e32 v121, v38
	v_sub_f32_e32 v38, v52, v75
	v_exp_f32_e32 v46, v38
	v_sub_f32_e32 v38, v53, v75
	v_exp_f32_e32 v48, v38
	v_sub_f32_e32 v38, v50, v75
	v_exp_f32_e32 v222, v38
	v_sub_f32_e32 v38, v51, v75
	v_exp_f32_e32 v218, v38
	v_add_f32_e32 v47, v77, v81
	v_add_f32_e32 v49, v85, v121
	v_pk_add_f32 v[38:39], v[46:47], v[48:49]
	v_pk_add_f32 v[42:43], v[222:223], v[218:219]
	s_nop 0
	v_pk_add_f32 v[38:39], v[38:39], v[42:43]
	s_nop 0
	v_pk_add_f32 v[52:53], v[38:39], v[38:39] op_sel_hi:[0,1]
	v_sub_f32_e32 v38, v56, v75
	v_exp_f32_e32 v50, v38
	v_sub_f32_e32 v38, v57, v75
	v_exp_f32_e32 v56, v38
	v_sub_f32_e32 v38, v54, v75
	v_exp_f32_e32 v51, v38
	v_sub_f32_e32 v38, v55, v75
	v_exp_f32_e32 v57, v38
	s_nop 0
	v_pk_add_f32 v[38:39], v[50:51], v[56:57]
	s_nop 0
	v_pk_add_f32 v[54:55], v[38:39], v[38:39] op_sel_hi:[0,1]
	v_sub_f32_e32 v38, v60, v75
	v_exp_f32_e32 v49, v38
	v_sub_f32_e32 v38, v61, v75
	v_exp_f32_e32 v123, v38
	v_sub_f32_e32 v38, v58, v75
	v_exp_f32_e32 v127, v38
	v_sub_f32_e32 v38, v59, v75
	v_exp_f32_e32 v131, v38
	v_sub_f32_e32 v38, v152, v75
	v_exp_f32_e32 v58, v38
	v_sub_f32_e32 v38, v153, v75
	v_exp_f32_e32 v60, v38
	v_sub_f32_e32 v38, v150, v75
	v_exp_f32_e32 v54, v38
	v_sub_f32_e32 v38, v151, v75
	v_exp_f32_e32 v52, v38
	v_add_f32_e32 v59, v49, v123
	v_add_f32_e32 v61, v127, v131
	v_pk_add_f32 v[38:39], v[58:59], v[60:61]
	v_pk_add_f32 v[42:43], v[54:55], v[52:53]
	s_nop 0
	v_pk_add_f32 v[38:39], v[38:39], v[42:43]
	s_nop 0
	v_pk_add_f32 v[150:151], v[38:39], v[38:39] op_sel_hi:[0,1]
	v_sub_f32_e32 v38, v156, v75
	v_exp_f32_e32 v152, v38
	v_sub_f32_e32 v38, v157, v75
	v_exp_f32_e32 v156, v38
	v_sub_f32_e32 v38, v154, v75
	v_exp_f32_e32 v153, v38
	v_sub_f32_e32 v38, v155, v75
	v_exp_f32_e32 v157, v38
	s_nop 0
	v_pk_add_f32 v[38:39], v[152:153], v[156:157]
	s_nop 0
	v_pk_add_f32 v[154:155], v[38:39], v[38:39] op_sel_hi:[0,1]
	v_sub_f32_e32 v38, v160, v75
	v_exp_f32_e32 v55, v38
	v_sub_f32_e32 v38, v161, v75
	v_exp_f32_e32 v59, v38
	v_sub_f32_e32 v38, v158, v75
	v_exp_f32_e32 v61, v38
	v_sub_f32_e32 v38, v159, v75
	v_exp_f32_e32 v135, v38
	v_sub_f32_e32 v38, v204, v75
	v_exp_f32_e32 v158, v38
	v_sub_f32_e32 v38, v205, v75
	v_exp_f32_e32 v160, v38
	v_sub_f32_e32 v38, v202, v75
	v_exp_f32_e32 v154, v38
	v_sub_f32_e32 v38, v203, v75
	v_exp_f32_e32 v150, v38
	v_add_f32_e32 v159, v55, v59
	v_add_f32_e32 v161, v61, v135
	v_pk_add_f32 v[38:39], v[158:159], v[160:161]
	v_pk_add_f32 v[42:43], v[154:155], v[150:151]
	s_nop 0
	v_pk_add_f32 v[38:39], v[38:39], v[42:43]
	s_nop 0
	v_pk_add_f32 v[202:203], v[38:39], v[38:39] op_sel_hi:[0,1]
	v_sub_f32_e32 v38, v208, v75
	v_exp_f32_e32 v204, v38
	v_sub_f32_e32 v38, v209, v75
	v_exp_f32_e32 v208, v38
	v_sub_f32_e32 v38, v206, v75
	v_exp_f32_e32 v205, v38
	v_sub_f32_e32 v38, v207, v75
	v_exp_f32_e32 v209, v38
	s_nop 0
	v_pk_add_f32 v[38:39], v[204:205], v[208:209]
	s_nop 0
	v_pk_add_f32 v[206:207], v[38:39], v[38:39] op_sel_hi:[0,1]
	v_sub_f32_e32 v38, v214, v75
	v_exp_f32_e32 v151, v38
	v_sub_f32_e32 v38, v215, v75
	v_exp_f32_e32 v155, v38
	v_sub_f32_e32 v38, v212, v75
	v_exp_f32_e32 v212, v34
	v_sub_f32_e32 v34, v35, v75
	v_exp_f32_e32 v159, v38
	v_sub_f32_e32 v38, v213, v75
	v_exp_f32_e32 v214, v34
	v_sub_f32_e32 v34, v36, v75
	v_exp_f32_e32 v161, v38
	v_exp_f32_e32 v206, v34
	v_sub_f32_e32 v34, v37, v75
	v_exp_f32_e32 v202, v34
	v_add_f32_e32 v213, v151, v155
	v_add_f32_e32 v215, v159, v161
	v_pk_add_f32 v[34:35], v[212:213], v[214:215]
	v_pk_add_f32 v[36:37], v[206:207], v[202:203]
	v_cvt_pk_bf16_f32 v38, v40, v216
	v_cvt_pk_bf16_f32 v39, v41, v217
	v_cvt_pk_bf16_f32 v40, v44, v220
	v_cvt_pk_bf16_f32 v41, v45, v221
	v_cvt_pk_bf16_f32 v42, v77, v81
	s_nop 0
	v_pk_add_f32 v[34:35], v[34:35], v[36:37]
	v_cvt_pk_bf16_f32 v43, v85, v121
	v_cvt_pk_bf16_f32 v44, v46, v48
	v_cvt_pk_bf16_f32 v45, v222, v218
	v_cvt_pk_bf16_f32 v46, v50, v56
	v_cvt_pk_bf16_f32 v47, v51, v57
	s_nop 0
	v_add_f32_e32 v34, v34, v35
	ds_bpermute_b32 v35, v113, v34
	v_cvt_pk_bf16_f32 v48, v49, v123
	v_cvt_pk_bf16_f32 v49, v127, v131
	v_cvt_pk_bf16_f32 v50, v58, v60
	v_cvt_pk_bf16_f32 v51, v54, v52
	s_waitcnt lgkmcnt(0)
	v_add_f32_e32 v34, v34, v35
	ds_bpermute_b32 v35, v115, v34
	v_cvt_pk_bf16_f32 v52, v152, v156
	v_cvt_pk_bf16_f32 v53, v153, v157
	v_cvt_pk_bf16_f32 v54, v55, v59
	v_cvt_pk_bf16_f32 v55, v61, v135
	s_waitcnt lgkmcnt(0)
	v_add_f32_e32 v34, v34, v35
	v_fma_f32 v35, v90, s65, -v75
	v_exp_f32_e32 v35, v35
	v_cvt_pk_bf16_f32 v56, v158, v160
	v_cvt_pk_bf16_f32 v57, v154, v150
	v_cvt_pk_bf16_f32 v58, v204, v208
	v_cvt_pk_bf16_f32 v59, v205, v209
	v_cvt_pk_bf16_f32 v60, v151, v155
	s_nop 0
	v_add_f32_e32 v75, v35, v34
	v_div_scale_f32 v77, s[0:1], v75, v75, 1.0
	v_rcp_f32_e32 v81, v77
	v_cvt_pk_bf16_f32 v61, v159, v161
	v_cvt_pk_bf16_f32 v34, v212, v214
	v_cvt_pk_bf16_f32 v35, v206, v202
	v_cvt_pk_bf16_f32 v36, v91, v91
	v_cvt_pk_bf16_f32 v37, v91, v91
	s_nop 0
	v_fma_f32 v85, -v77, v81, 1.0
	v_fmac_f32_e32 v81, v85, v81
	v_div_scale_f32 v85, vcc, 1.0, v75, 1.0
	v_mul_f32_e32 v90, v85, v81
	v_fma_f32 v121, -v77, v90, v85
	v_fmac_f32_e32 v90, v121, v81
	v_fma_f32 v77, -v77, v90, v85
	v_div_fmas_f32 v77, v77, v81, v90
	v_div_fixup_f32 v90, v77, v75, 1.0
	v_add_u32_e32 v75, v191, v164
	v_add_u32_e32 v75, 0xd800, v75
	ds_read2_b64 v[150:153], v75 offset0:160 offset1:164
	ds_read2_b64 v[154:157], v75 offset0:168 offset1:172
	s_waitcnt lgkmcnt(1)
	v_mfma_f32_16x16x32_bf16 v[150:153], v[150:153], v[38:41], 0
	s_waitcnt lgkmcnt(0)
	v_mfma_f32_16x16x32_bf16 v[150:153], v[154:157], v[42:45], v[150:153]
	ds_read2_b64 v[154:157], v75 offset0:176 offset1:180
	s_waitcnt lgkmcnt(0)
	v_mfma_f32_16x16x32_bf16 v[150:153], v[154:157], v[46:49], v[150:153]
	ds_read2_b64 v[154:157], v75 offset0:184 offset1:188
	s_waitcnt lgkmcnt(0)
	v_mfma_f32_16x16x32_bf16 v[150:153], v[154:157], v[50:53], v[150:153]
	ds_read2_b64 v[154:157], v75 offset0:192 offset1:196
	s_waitcnt lgkmcnt(0)
	v_mfma_f32_16x16x32_bf16 v[150:153], v[154:157], v[54:57], v[150:153]
	ds_read2_b64 v[154:157], v75 offset0:200 offset1:204
	s_waitcnt lgkmcnt(0)
	v_mfma_f32_16x16x32_bf16 v[150:153], v[154:157], v[58:61], v[150:153]
	ds_read2_b64 v[154:157], v75 offset0:208 offset1:212
	v_add_u32_e32 v75, 0x9000, v190
	ds_read2_b64 v[158:161], v75 offset0:120 offset1:124
	s_waitcnt lgkmcnt(1)
	v_mfma_f32_16x16x32_bf16 v[152:155], v[154:157], v[34:37], v[150:153]
	s_nop 7
	v_pk_mul_f32 v[150:151], v[90:91], v[154:155] op_sel_hi:[0,1]
	ds_read2_b64 v[154:157], v75 offset0:112 offset1:116
	s_waitcnt lgkmcnt(0)
	v_mfma_f32_16x16x32_bf16 v[154:157], v[154:157], v[38:41], 0
	v_mul_f32_e64 v152, v90, v152
	v_mul_f32_e64 v153, v90, v153
	v_mfma_f32_16x16x32_bf16 v[154:157], v[158:161], v[42:45], v[154:157]
	ds_read2_b64 v[158:161], v75 offset0:128 offset1:132
	s_waitcnt lgkmcnt(0)
	v_mfma_f32_16x16x32_bf16 v[154:157], v[158:161], v[46:49], v[154:157]
	ds_read2_b64 v[158:161], v75 offset0:136 offset1:140
	s_waitcnt lgkmcnt(0)
	v_mfma_f32_16x16x32_bf16 v[154:157], v[158:161], v[50:53], v[154:157]
	ds_read2_b64 v[158:161], v75 offset0:144 offset1:148
	s_waitcnt lgkmcnt(0)
	v_mfma_f32_16x16x32_bf16 v[154:157], v[158:161], v[54:57], v[154:157]
	ds_read2_b64 v[158:161], v75 offset0:152 offset1:156
	s_waitcnt lgkmcnt(0)
	v_mfma_f32_16x16x32_bf16 v[154:157], v[158:161], v[58:61], v[154:157]
	ds_read2_b64 v[158:161], v75 offset0:160 offset1:164
	v_add_u32_e32 v75, 0xb000, v190
	ds_read2_b64 v[202:205], v75 offset0:40 offset1:44
	s_waitcnt lgkmcnt(1)
	v_mfma_f32_16x16x32_bf16 v[154:157], v[158:161], v[34:37], v[154:157]
	ds_read2_b64 v[158:161], v75 offset0:32 offset1:36
	s_nop 6
	v_pk_mul_f32 v[154:155], v[90:91], v[154:155] op_sel_hi:[0,1]
	s_waitcnt lgkmcnt(0)
	v_mfma_f32_16x16x32_bf16 v[158:161], v[158:161], v[38:41], 0
	v_mul_f32_e64 v156, v90, v156
	v_mul_f32_e64 v157, v90, v157
	v_mfma_f32_16x16x32_bf16 v[158:161], v[202:205], v[42:45], v[158:161]
	ds_read2_b64 v[202:205], v75 offset0:48 offset1:52
	s_waitcnt lgkmcnt(0)
	v_mfma_f32_16x16x32_bf16 v[158:161], v[202:205], v[46:49], v[158:161]
	ds_read2_b64 v[202:205], v75 offset0:56 offset1:60
	s_waitcnt lgkmcnt(0)
	v_mfma_f32_16x16x32_bf16 v[158:161], v[202:205], v[50:53], v[158:161]
	ds_read2_b64 v[202:205], v75 offset0:64 offset1:68
	s_waitcnt lgkmcnt(0)
	v_mfma_f32_16x16x32_bf16 v[158:161], v[202:205], v[54:57], v[158:161]
	ds_read2_b64 v[202:205], v75 offset0:72 offset1:76
	s_waitcnt lgkmcnt(0)
	v_mfma_f32_16x16x32_bf16 v[158:161], v[202:205], v[58:61], v[158:161]
	ds_read2_b64 v[202:205], v75 offset0:80 offset1:84
	v_add_u32_e32 v75, 0xc800, v190
	s_waitcnt lgkmcnt(0)
	v_mfma_f32_16x16x32_bf16 v[202:205], v[202:205], v[34:37], v[158:161]
	s_nop 7
	v_pk_mul_f32 v[158:159], v[90:91], v[204:205] op_sel_hi:[0,1]
	v_pk_mul_f32 v[160:161], v[90:91], v[202:203] op_sel_hi:[0,1]
	ds_read2_b64 v[202:205], v75 offset0:208 offset1:212
	s_waitcnt lgkmcnt(0)
	v_mfma_f32_16x16x32_bf16 v[38:41], v[202:205], v[38:41], 0
	ds_read2_b64 v[202:205], v75 offset0:216 offset1:220
	s_waitcnt lgkmcnt(0)
	v_mfma_f32_16x16x32_bf16 v[38:41], v[202:205], v[42:45], v[38:41]
	ds_read2_b64 v[42:45], v75 offset0:224 offset1:228
	s_waitcnt lgkmcnt(0)
	v_mfma_f32_16x16x32_bf16 v[38:41], v[42:45], v[46:49], v[38:41]
	ds_read2_b64 v[42:45], v75 offset0:232 offset1:236
	s_waitcnt lgkmcnt(0)
	v_mfma_f32_16x16x32_bf16 v[38:41], v[42:45], v[50:53], v[38:41]
	ds_read2_b64 v[42:45], v75 offset0:240 offset1:244
	s_waitcnt lgkmcnt(0)
	v_mfma_f32_16x16x32_bf16 v[38:41], v[42:45], v[54:57], v[38:41]
	ds_read2_b64 v[42:45], v75 offset0:248 offset1:252
	s_waitcnt lgkmcnt(0)
	v_mfma_f32_16x16x32_bf16 v[38:41], v[42:45], v[58:61], v[38:41]
	v_add_u32_e32 v42, 0xd000, v190
	ds_read2_b64 v[42:45], v42 offset1:4
	s_waitcnt lgkmcnt(0)
	v_mfma_f32_16x16x32_bf16 v[34:37], v[42:45], v[34:37], v[38:41]
	v_mov_b32_e32 v42, v147
	v_mov_b32_e32 v43, v63
	v_pk_mul_f32 v[42:43], v[42:43], v[42:43]
	s_nop 4
	v_pk_mul_f32 v[38:39], v[90:91], v[36:37] op_sel_hi:[0,1]
	v_mov_b32_e32 v36, v149
	v_mov_b32_e32 v37, v65
	v_pk_mul_f32 v[40:41], v[90:91], v[34:35] op_sel_hi:[0,1]
	v_mov_b32_e32 v34, v148
	v_mov_b32_e32 v35, v64
	v_pk_mul_f32 v[36:37], v[36:37], v[36:37]
	s_nop 0
	v_pk_fma_f32 v[34:35], v[34:35], v[34:35], v[36:37]
	v_mov_b32_e32 v36, v146
	v_mov_b32_e32 v37, v62
	v_pk_fma_f32 v[36:37], v[36:37], v[36:37], v[42:43]
	v_pk_mul_f32 v[42:43], v[66:67], v[66:67]
	v_pk_add_f32 v[34:35], v[34:35], v[36:37]
	v_pk_mul_f32 v[36:37], v[68:69], v[68:69]
	v_pk_add_f32 v[34:35], v[34:35], v[34:35] op_sel:[0,1] op_sel_hi:[1,0]
	v_pk_mov_b32 v[44:45], v[42:43], v[36:37] op_sel:[1,0]
	v_mov_b32_e32 v43, v37
	v_pk_add_f32 v[36:37], v[44:45], v[42:43]
	v_mul_f32_e32 v42, v152, v152
	v_mul_f32_e32 v43, v153, v153
	v_pk_add_f32 v[36:37], v[36:37], v[36:37] op_sel:[0,1] op_sel_hi:[1,0]
	v_mov_b32_e32 v35, v42
	v_mov_b32_e32 v37, v43
	v_pk_add_f32 v[34:35], v[34:35], v[36:37]
	v_mul_f32_e32 v36, v73, v73
	v_mul_f32_e32 v42, v71, v71
	v_mul_f32_e32 v44, v150, v150
	v_mul_f32_e32 v45, v151, v151
	v_pk_fma_f32 v[36:37], v[72:73], v[72:73], v[36:37] op_sel_hi:[1,1,0]
	v_pk_fma_f32 v[42:43], v[70:71], v[70:71], v[42:43] op_sel_hi:[1,1,0]
	v_mov_b32_e32 v37, v44
	v_mov_b32_e32 v43, v45
	v_pk_add_f32 v[36:37], v[36:37], v[42:43]
	v_pk_mul_f32 v[42:43], v[154:155], v[154:155]
	v_pk_add_f32 v[34:35], v[34:35], v[36:37]
	v_pk_mul_f32 v[36:37], v[156:157], v[156:157]
	v_pk_add_f32 v[34:35], v[34:35], v[34:35] op_sel:[0,1] op_sel_hi:[1,0]
	v_pk_mov_b32 v[44:45], v[42:43], v[36:37] op_sel:[1,0]
	v_mov_b32_e32 v43, v37
	v_pk_add_f32 v[36:37], v[44:45], v[42:43]
	v_mul_f32_e32 v42, v40, v40
	v_mul_f32_e32 v43, v41, v41
	v_pk_add_f32 v[36:37], v[36:37], v[36:37] op_sel:[0,1] op_sel_hi:[1,0]
	v_mov_b32_e32 v35, v42
	v_mov_b32_e32 v37, v43
	v_pk_add_f32 v[34:35], v[34:35], v[36:37]
	v_mul_f32_e32 v36, v161, v161
	v_mul_f32_e32 v42, v159, v159
	v_mul_f32_e32 v44, v38, v38
	v_mul_f32_e32 v45, v39, v39
	v_pk_fma_f32 v[36:37], v[160:161], v[160:161], v[36:37] op_sel_hi:[1,1,0]
	v_pk_fma_f32 v[42:43], v[158:159], v[158:159], v[42:43] op_sel_hi:[1,1,0]
	v_mov_b32_e32 v37, v44
	v_mov_b32_e32 v43, v45
	v_pk_add_f32 v[36:37], v[36:37], v[42:43]
	s_nop 0
	v_pk_add_f32 v[34:35], v[34:35], v[36:37]
	s_nop 0
	v_add_f32_e32 v34, v34, v35
	ds_bpermute_b32 v35, v113, v34
	s_waitcnt lgkmcnt(0)
	v_add_f32_e32 v34, v34, v35
	ds_bpermute_b32 v35, v115, v34
	s_waitcnt lgkmcnt(0)
	v_add_f32_e32 v34, v34, v35
	ds_bpermute_b32 v35, v117, v34
	s_waitcnt lgkmcnt(0)
	v_add_f32_e32 v34, v34, v35
	ds_bpermute_b32 v35, v119, v34
	s_waitcnt lgkmcnt(0)
	v_add_f32_e32 v34, v34, v35
	v_fmamk_f32 v34, v34, 0x3b000000, v185
	v_cmp_gt_f32_e32 vcc, s66, v34
	v_mul_f32_e32 v35, 0x4b800000, v34
	s_nop 0
	v_cndmask_b32_e32 v34, v34, v35, vcc
	v_rsq_f32_e32 v34, v34
	s_nop 0
	v_mul_f32_e32 v35, 0x45800000, v34
	v_cndmask_b32_e32 v42, v34, v35, vcc
	global_load_dwordx4 v[34:37], v[98:99], off
	v_pk_mul_f32 v[44:45], v[148:149], v[42:43] op_sel_hi:[1,0]
	v_pk_mul_f32 v[46:47], v[146:147], v[42:43] op_sel_hi:[1,0]
	v_pk_mul_f32 v[48:49], v[62:63], v[42:43] op_sel_hi:[1,0]
	v_pk_mul_f32 v[40:41], v[40:41], v[42:43] op_sel_hi:[1,0]
	s_waitcnt vmcnt(0)
	v_pk_mul_f32 v[34:35], v[34:35], v[44:45]
	v_pk_mul_f32 v[36:37], v[36:37], v[46:47]
	v_cvt_pk_bf16_f32 v34, v34, v35
	s_nop 0
	v_cvt_pk_bf16_f32 v35, v36, v37
	v_pk_mul_f32 v[36:37], v[64:65], v[42:43] op_sel_hi:[1,0]
	v_pk_mul_f32 v[46:47], v[226:227], v[48:49]
	v_pk_mul_f32 v[36:37], v[224:225], v[36:37]
	v_lshl_add_u64 v[44:45], v[138:139], 0, s[24:25]
	v_cvt_pk_bf16_f32 v36, v36, v37
	v_cvt_pk_bf16_f32 v37, v46, v47
	v_pk_mul_f32 v[46:47], v[68:69], v[42:43] op_sel_hi:[1,0]
	v_permlane16_swap_b32_e32 v34, v36
	v_permlane16_swap_b32_e32 v35, v37
	global_store_dwordx4 v[44:45], v[34:37], off
	s_nop 0
	v_pk_mul_f32 v[44:45], v[66:67], v[42:43] op_sel_hi:[1,0]
	v_pk_mul_f32 v[48:49], v[70:71], v[42:43] op_sel_hi:[1,0]
	v_pk_mul_f32 v[34:35], v[228:229], v[44:45]
	v_pk_mul_f32 v[36:37], v[230:231], v[46:47]
	v_cvt_pk_bf16_f32 v34, v34, v35
	s_nop 0
	v_cvt_pk_bf16_f32 v35, v36, v37
	v_pk_mul_f32 v[36:37], v[72:73], v[42:43] op_sel_hi:[1,0]
	v_pk_mul_f32 v[46:47], v[234:235], v[48:49]
	v_pk_mul_f32 v[36:37], v[232:233], v[36:37]
	v_lshl_add_u64 v[44:45], v[140:141], 0, s[24:25]
	v_cvt_pk_bf16_f32 v36, v36, v37
	v_cvt_pk_bf16_f32 v37, v46, v47
	v_pk_mul_f32 v[46:47], v[150:151], v[42:43] op_sel_hi:[1,0]
	v_permlane16_swap_b32_e32 v34, v36
	v_permlane16_swap_b32_e32 v35, v37
	global_store_dwordx4 v[44:45], v[34:37], off
	s_nop 0
	v_pk_mul_f32 v[44:45], v[152:153], v[42:43] op_sel_hi:[1,0]
	v_pk_mul_f32 v[48:49], v[156:157], v[42:43] op_sel_hi:[1,0]
	v_pk_mul_f32 v[34:35], v[44:45], v[236:237]
	v_pk_mul_f32 v[36:37], v[46:47], v[238:239]
	v_cvt_pk_bf16_f32 v34, v34, v35
	s_nop 0
	v_cvt_pk_bf16_f32 v35, v36, v37
	v_pk_mul_f32 v[36:37], v[154:155], v[42:43] op_sel_hi:[1,0]
	v_pk_mul_f32 v[46:47], v[48:49], v[242:243]
	v_pk_mul_f32 v[36:37], v[36:37], v[240:241]
	v_lshl_add_u64 v[44:45], v[142:143], 0, s[24:25]
	v_cvt_pk_bf16_f32 v36, v36, v37
	v_cvt_pk_bf16_f32 v37, v46, v47
	v_pk_mul_f32 v[46:47], v[158:159], v[42:43] op_sel_hi:[1,0]
	v_permlane16_swap_b32_e32 v34, v36
	v_permlane16_swap_b32_e32 v35, v37
	global_store_dwordx4 v[44:45], v[34:37], off
	s_nop 0
	v_pk_mul_f32 v[44:45], v[160:161], v[42:43] op_sel_hi:[1,0]
	v_pk_mul_f32 v[42:43], v[38:39], v[42:43] op_sel_hi:[1,0]
	v_pk_mul_f32 v[36:37], v[46:47], v[246:247]
	v_pk_mul_f32 v[34:35], v[44:45], v[244:245]
	s_nop 0
	v_cvt_pk_bf16_f32 v34, v34, v35
	v_cvt_pk_bf16_f32 v35, v36, v37
	v_pk_mul_f32 v[38:39], v[42:43], v[250:251]
	v_pk_mul_f32 v[36:37], v[40:41], v[248:249]
	s_nop 0
	v_cvt_pk_bf16_f32 v36, v36, v37
	v_cvt_pk_bf16_f32 v37, v38, v39
	v_lshl_add_u64 v[38:39], v[144:145], 0, s[24:25]
	s_add_u32 s24, s24, 0x2000
	s_addc_u32 s25, s25, 0
	v_permlane16_swap_b32_e32 v34, v36
	v_permlane16_swap_b32_e32 v35, v37
	s_cmpk_eq_i32 s24, 0x4000
	global_store_dwordx4 v[38:39], v[34:37], off
	s_cbranch_scc0 .LBB0_414
	s_mov_b64 s[0:1], 0
